# EVENB: the item's 8 scan-state row loads issued at item start (staged in free registers) instead of between the MFMAs
# baseline (speedup 1.0000x reference)
.Levenb_nopf:
	global_load_dwordx4 v[216:219], v[84:85], off offset:-64
	global_load_dwordx4 v[220:223], v[84:85], off offset:-128
	global_load_dwordx4 v[156:159], v[84:85], off offset:-96
	global_load_dwordx4 v[160:163], v[84:85], off offset:-32
	global_load_dwordx4 v[164:167], v[84:85], off
	global_load_dwordx4 v[170:173], v[84:85], off offset:32
	global_load_dwordx4 v[228:231], v[84:85], off offset:64
	global_load_dwordx4 v[234:237], v[84:85], off offset:96
	s_waitcnt lgkmcnt(0)
	v_mul_f32_e32 v76, s4, v122
	v_exp_f32_e32 v136, v76
	v_mul_f32_e32 v76, s4, v124
	v_exp_f32_e32 v137, v76
	v_mul_f32_e32 v76, s4, v126
	v_mul_f32_e32 v87, s4, v128
	v_exp_f32_e32 v138, v76
	v_exp_f32_e32 v139, v87
	v_lshlrev_b32_e32 v40, 16, v32
	v_and_b32_e32 v41, 0xffff0000, v32
	v_lshlrev_b32_e32 v42, 16, v36
	v_and_b32_e32 v43, 0xffff0000, v36
	v_mov_b32_e32 v44, v28
	v_mov_b32_e32 v45, v30
	v_mov_b32_e32 v30, v29
	v_lshlrev_b32_e32 v28, 16, v33
	v_and_b32_e32 v29, 0xffff0000, v33
	v_lshlrev_b32_e32 v32, 16, v37
	v_and_b32_e32 v33, 0xffff0000, v37
	v_mov_b32_e32 v47, v26
	v_mov_b32_e32 v26, v25
	v_lshlrev_b32_e32 v36, 16, v38
	v_and_b32_e32 v37, 0xffff0000, v38
	v_mov_b32_e32 v48, v16
	v_mov_b32_e32 v49, v18
	v_mov_b32_e32 v18, v17
	v_mov_b32_e32 v46, v24
	v_lshlrev_b32_e32 v24, 16, v34
	v_and_b32_e32 v25, 0xffff0000, v34
	v_lshlrev_b32_e32 v16, 16, v35
	v_and_b32_e32 v17, 0xffff0000, v35
	v_lshlrev_b32_e32 v34, 16, v39
	v_and_b32_e32 v35, 0xffff0000, v39
	v_mov_b32_e32 v50, v8
	v_mov_b32_e32 v51, v10
	v_mov_b32_e32 v10, v9
	v_pk_mul_f32 v[8:9], v[30:31], v[42:43]
	v_pk_mul_f32 v[38:39], v[44:45], v[42:43]
	v_pk_mul_f32 v[42:43], v[26:27], v[32:33]
	v_pk_mul_f32 v[52:53], v[18:19], v[36:37]
	v_pk_mul_f32 v[36:37], v[48:49], v[36:37]
	v_lshlrev_b32_e32 v58, 16, v12
	v_and_b32_e32 v59, 0xffff0000, v12
	v_pk_fma_f32 v[8:9], v[44:45], v[40:41], v[8:9] neg_lo:[0,0,1] neg_hi:[0,0,1]
	v_pk_fma_f32 v[38:39], v[30:31], v[40:41], v[38:39]
	v_pk_fma_f32 v[40:41], v[46:47], v[28:29], v[42:43] neg_lo:[0,0,1] neg_hi:[0,0,1]
	v_pk_fma_f32 v[42:43], v[48:49], v[24:25], v[52:53] neg_lo:[0,0,1] neg_hi:[0,0,1]
	v_pk_fma_f32 v[24:25], v[18:19], v[24:25], v[36:37]
	v_lshlrev_b32_e32 v12, 16, v13
	v_and_b32_e32 v13, 0xffff0000, v13
	v_pk_mul_f32 v[32:33], v[46:47], v[32:33]
	v_lshlrev_b32_e32 v56, 16, v20
	v_and_b32_e32 v57, 0xffff0000, v20
	v_cvt_pk_bf16_f32 v36, v38, v39
	v_cvt_pk_bf16_f32 v38, v24, v25
	v_lshlrev_b32_e32 v20, 16, v21
	v_and_b32_e32 v21, 0xffff0000, v21
	v_pk_mul_f32 v[24:25], v[26:27], v[12:13]
	v_pk_mul_f32 v[12:13], v[46:47], v[12:13]
	v_pk_fma_f32 v[28:29], v[26:27], v[28:29], v[32:33]
	v_pk_fma_f32 v[12:13], v[26:27], v[20:21], v[12:13]
	v_lshlrev_b32_e32 v26, 16, v14
	v_and_b32_e32 v27, 0xffff0000, v14
	v_cvt_pk_bf16_f32 v37, v28, v29
	v_pk_fma_f32 v[24:25], v[46:47], v[20:21], v[24:25] neg_lo:[0,0,1] neg_hi:[0,0,1]
	v_pk_mul_f32 v[20:21], v[12:13], s[40:41] op_sel_hi:[1,0]
	v_lshlrev_b32_e32 v12, 16, v22
	v_and_b32_e32 v13, 0xffff0000, v22
	v_pk_mul_f32 v[28:29], v[18:19], v[26:27]
	v_pk_mul_f32 v[26:27], v[48:49], v[26:27]
	v_pk_mul_f32 v[54:55], v[10:11], v[34:35]
	v_pk_mul_f32 v[34:35], v[50:51], v[34:35]
	v_pk_fma_f32 v[28:29], v[48:49], v[12:13], v[28:29] neg_lo:[0,0,1] neg_hi:[0,0,1]
	v_pk_fma_f32 v[12:13], v[18:19], v[12:13], v[26:27]
	v_lshlrev_b32_e32 v14, 16, v15
	v_and_b32_e32 v15, 0xffff0000, v15
	v_pk_fma_f32 v[52:53], v[50:51], v[16:17], v[54:55] neg_lo:[0,0,1] neg_hi:[0,0,1]
	v_pk_fma_f32 v[16:17], v[10:11], v[16:17], v[34:35]
	v_pk_mul_f32 v[54:55], v[30:31], v[58:59]
	v_pk_mul_f32 v[18:19], v[12:13], s[40:41] op_sel_hi:[1,0]
	v_lshlrev_b32_e32 v12, 16, v23
	v_and_b32_e32 v13, 0xffff0000, v23
	v_pk_mul_f32 v[22:23], v[10:11], v[14:15]
	v_cvt_pk_bf16_f32 v32, v8, v9
	v_cvt_pk_bf16_f32 v39, v16, v17
	v_pk_fma_f32 v[8:9], v[44:45], v[56:57], v[54:55] neg_lo:[0,0,1] neg_hi:[0,0,1]
	v_pk_mul_f32 v[16:17], v[44:45], v[58:59]
	v_pk_fma_f32 v[22:23], v[50:51], v[12:13], v[22:23] neg_lo:[0,0,1] neg_hi:[0,0,1]
	v_pk_mul_f32 v[14:15], v[50:51], v[14:15]
	v_pk_mul_f32 v[8:9], v[8:9], s[40:41] op_sel_hi:[1,0]
	v_pk_fma_f32 v[16:17], v[30:31], v[56:57], v[16:17]
	v_pk_mul_f32 v[24:25], v[24:25], s[40:41] op_sel_hi:[1,0]
	v_pk_mul_f32 v[28:29], v[28:29], s[40:41] op_sel_hi:[1,0]
	v_pk_mul_f32 v[22:23], v[22:23], s[40:41] op_sel_hi:[1,0]
	v_pk_fma_f32 v[10:11], v[10:11], v[12:13], v[14:15]
	v_cvt_pk_bf16_f32 v33, v40, v41
	v_cvt_pk_bf16_f32 v34, v42, v43
	v_cvt_pk_bf16_f32 v35, v52, v53
	v_pk_mul_f32 v[16:17], v[16:17], s[40:41] op_sel_hi:[1,0]
	v_pk_mul_f32 v[26:27], v[10:11], s[40:41] op_sel_hi:[1,0]
	v_cvt_pk_bf16_f32 v8, v8, v9
	v_cvt_pk_bf16_f32 v9, v24, v25
	v_cvt_pk_bf16_f32 v10, v28, v29
	v_cvt_pk_bf16_f32 v11, v22, v23
	ds_write_b128 v90, v[32:35]
	ds_write_b128 v90, v[36:39] offset:128
	v_cvt_pk_bf16_f32 v12, v16, v17
	v_cvt_pk_bf16_f32 v13, v20, v21
	v_cvt_pk_bf16_f32 v14, v18, v19
	v_cvt_pk_bf16_f32 v15, v26, v27
	ds_write_b128 v90, v[8:11] offset:17408
	ds_write_b128 v90, v[12:15] offset:17536
	ds_write_b128 v90, v[0:3] offset:34816
	ds_write_b128 v90, v[4:7] offset:34944
	s_waitcnt lgkmcnt(0)
	s_barrier
	ds_read_b128 v[0:3], v91 offset:17408
	ds_read_b128 v[32:35], v94
	ds_read_b128 v[36:39], v91 offset:17440
	ds_read_b128 v[52:55], v94 offset:32
	s_waitcnt lgkmcnt(2)
	v_mfma_f32_32x32x16_bf16 v[16:31], v[0:3], v[32:35], 0
	ds_read_b128 v[0:3], v92 offset:17408
	ds_read_b128 v[40:43], v92 offset:17440
	s_waitcnt lgkmcnt(1)
	v_mfma_f32_32x32x16_bf16 v[0:15], v[0:3], v[32:35], 0
	v_mfma_f32_32x32x16_bf16 v[16:31], v[36:39], v[52:55], v[16:31]
	s_waitcnt lgkmcnt(0)
	v_mfma_f32_32x32x16_bf16 v[0:15], v[40:43], v[52:55], v[0:15]
	ds_read_b128 v[36:39], v91 offset:17472
	ds_read_b128 v[56:59], v94 offset:64
	ds_read_b128 v[40:43], v91 offset:17504
	ds_read_b128 v[60:63], v94 offset:96
	s_waitcnt lgkmcnt(2)
	v_mfma_f32_32x32x16_bf16 v[16:31], v[36:39], v[56:59], v[16:31]
	ds_read_b128 v[36:39], v92 offset:17472
	ds_read_b128 v[44:47], v92 offset:17504
	s_waitcnt lgkmcnt(1)
	v_mfma_f32_32x32x16_bf16 v[0:15], v[36:39], v[56:59], v[0:15]
	v_mfma_f32_32x32x16_bf16 v[16:31], v[40:43], v[60:63], v[16:31]
	ds_read_b128 v[36:39], v91 offset:17536
	ds_read_b128 v[64:67], v94 offset:128
	ds_read_b128 v[40:43], v91 offset:17568
	ds_read_b128 v[68:71], v94 offset:160
	s_waitcnt lgkmcnt(4)
	v_mfma_f32_32x32x16_bf16 v[0:15], v[44:47], v[60:63], v[0:15]
	s_waitcnt lgkmcnt(2)
	v_mfma_f32_32x32x16_bf16 v[16:31], v[36:39], v[64:67], v[16:31]
	ds_read_b128 v[36:39], v92 offset:17536
	ds_read_b128 v[44:47], v92 offset:17568
	s_waitcnt lgkmcnt(1)
	v_mfma_f32_32x32x16_bf16 v[0:15], v[36:39], v[64:67], v[0:15]
	v_mfma_f32_32x32x16_bf16 v[16:31], v[40:43], v[68:71], v[16:31]
	ds_read_b128 v[36:39], v91 offset:17600
	ds_read_b128 v[72:75], v94 offset:192
	ds_read_b128 v[40:43], v91 offset:17632
	ds_read_b128 v[48:51], v94 offset:224
	s_waitcnt lgkmcnt(4)
	v_mfma_f32_32x32x16_bf16 v[0:15], v[44:47], v[68:71], v[0:15]
	s_waitcnt lgkmcnt(2)
	v_mfma_f32_32x32x16_bf16 v[16:31], v[36:39], v[72:75], v[16:31]
	ds_read_b128 v[36:39], v92 offset:17600
	ds_read_b128 v[44:47], v92 offset:17632
	s_waitcnt vmcnt(0)
	s_nop 1
	v_mov_b32_e32 v76, v216
	v_mov_b32_e32 v77, v217
	v_mov_b32_e32 v78, v218
	v_mov_b32_e32 v79, v219
	s_waitcnt lgkmcnt(1)
	v_mfma_f32_32x32x16_bf16 v[0:15], v[36:39], v[72:75], v[0:15]
	v_mul_f32_e32 v36, s4, v98
	v_mul_f32_e32 v37, s4, v100
	v_exp_f32_e32 v36, v36
	v_exp_f32_e32 v37, v37
	v_mul_f32_e32 v38, s4, v99
	v_exp_f32_e32 v38, v38
	v_mfma_f32_32x32x16_bf16 v[16:31], v[40:43], v[48:51], v[16:31]
	s_waitcnt lgkmcnt(0)
	v_mfma_f32_32x32x16_bf16 v[0:15], v[44:47], v[48:51], v[0:15]
	s_nop 9
	v_mul_f32_e64 v16, v36, v16
	v_mul_f32_e64 v17, v37, v17
	v_mul_f32_e32 v36, s4, v101
	v_exp_f32_e32 v39, v36
	v_mul_f32_e32 v36, s4, v102
	v_exp_f32_e32 v40, v36
	v_mul_f32_e32 v36, s4, v104
	v_exp_f32_e32 v41, v36
	v_pk_mul_f32 v[36:37], v[38:39], v[0:1]
	v_mul_f32_e32 v0, s4, v103
	v_mul_f32_e32 v1, s4, v105
	v_exp_f32_e32 v0, v0
	v_exp_f32_e32 v1, v1
	v_mul_f32_e32 v38, s4, v106
	v_pk_mul_f32 v[18:19], v[40:41], v[18:19]
	v_exp_f32_e32 v40, v38
	v_mul_f32_e32 v38, s4, v108
	v_exp_f32_e32 v41, v38
	v_pk_mul_f32 v[38:39], v[0:1], v[2:3]
	v_mul_f32_e32 v0, s4, v107
	v_mul_f32_e32 v1, s4, v109
	v_exp_f32_e32 v0, v0
	v_exp_f32_e32 v1, v1
	v_mul_f32_e32 v2, s4, v110
	v_exp_f32_e32 v42, v2
	v_mul_f32_e32 v2, s4, v111
	v_exp_f32_e32 v44, v2
	v_mul_f32_e32 v2, s4, v112
	v_exp_f32_e32 v43, v2
	v_mul_f32_e32 v2, s4, v113
	v_pk_mul_f32 v[20:21], v[40:41], v[20:21]
	v_exp_f32_e32 v45, v2
	v_pk_mul_f32 v[40:41], v[0:1], v[4:5]
	s_nop 1
	v_mov_b32_e32 v0, v220
	v_mov_b32_e32 v1, v221
	v_mov_b32_e32 v2, v222
	v_mov_b32_e32 v3, v223
	v_mul_f32_e32 v4, s4, v114
	v_pk_mul_f32 v[46:47], v[42:43], v[22:23]
	v_exp_f32_e32 v22, v4
	v_mul_f32_e32 v4, s4, v116
	v_pk_mul_f32 v[42:43], v[44:45], v[6:7]
	v_exp_f32_e32 v23, v4
	s_nop 1
	v_mov_b32_e32 v4, v156
	v_mov_b32_e32 v5, v157
	v_mov_b32_e32 v6, v158
	v_mov_b32_e32 v7, v159
	v_mul_f32_e32 v44, s4, v118
	v_mul_f32_e32 v45, s4, v120
	v_exp_f32_e32 v44, v44
	v_exp_f32_e32 v45, v45
	v_pk_mul_f32 v[140:141], v[22:23], v[24:25]
	v_pk_mul_f32 v[144:145], v[136:137], v[28:29]
	v_pk_mul_f32 v[146:147], v[138:139], v[30:31]
	v_pk_mul_f32 v[142:143], v[44:45], v[26:27]
	ds_read_u16 v22, v130 offset:34816
	ds_read_u16 v23, v130 offset:35088
	ds_read_u16 v45, v130 offset:39712
	ds_read_u16 v87, v130 offset:39984
	ds_read_u16 v136, v130 offset:41344
	ds_read_u16 v137, v130 offset:41616
	ds_read_u16 v138, v130 offset:41888
	ds_read_u16 v139, v130 offset:42160
	s_waitcnt lgkmcnt(6)
	v_lshl_or_b32 v22, v23, 16, v22
	ds_read_u16 v23, v131 offset:34816
	ds_read_u16 v24, v131 offset:35088
	ds_read_u16 v25, v132 offset:34816
	ds_read_u16 v26, v132 offset:35088
	ds_read_u16 v27, v133 offset:34816
	ds_read_u16 v28, v133 offset:35088
	ds_read_u16 v44, v134 offset:34816
	ds_read_u16 v148, v134 offset:35088
	s_waitcnt lgkmcnt(6)
	v_lshl_or_b32 v23, v24, 16, v23
	s_waitcnt lgkmcnt(4)
	v_lshl_or_b32 v24, v26, 16, v25
	s_waitcnt lgkmcnt(2)
	v_lshl_or_b32 v25, v28, 16, v27
	v_cvt_pk_bf16_f32 v16, v16, v17
	v_cvt_pk_bf16_f32 v17, v18, v19
	v_cvt_pk_bf16_f32 v18, v20, v21
	v_cvt_pk_bf16_f32 v19, v46, v47
	s_waitcnt lgkmcnt(0)
	v_lshl_or_b32 v44, v148, 16, v44
	v_lshl_or_b32 v45, v87, 16, v45
	v_mfma_f32_32x32x16_bf16 v[16:31], v[22:25], v[16:19], 0
	v_lshl_or_b32 v46, v137, 16, v136
	v_lshl_or_b32 v47, v139, 16, v138
	v_cvt_pk_bf16_f32 v136, v140, v141
	v_cvt_pk_bf16_f32 v137, v142, v143
	v_cvt_pk_bf16_f32 v138, v144, v145
	v_cvt_pk_bf16_f32 v139, v146, v147
	v_cvt_pk_bf16_f32 v36, v36, v37
	v_cvt_pk_bf16_f32 v37, v38, v39
	v_mfma_f32_32x32x16_bf16 v[16:31], v[44:47], v[136:139], v[16:31]
	ds_read_u16 v44, v130 offset:43520
	ds_read_u16 v45, v130 offset:43792
	ds_read_u16 v46, v130 offset:44064
	ds_read_u16 v47, v130 offset:44336
	ds_read_u16 v87, v130 offset:45696
	ds_read_u16 v140, v130 offset:45968
	ds_read_u16 v141, v130 offset:46240
	ds_read_u16 v142, v130 offset:46512
	s_nop 1
	v_mov_b32_e32 v136, v160
	v_mov_b32_e32 v137, v161
	v_mov_b32_e32 v138, v162
	v_mov_b32_e32 v139, v163
	s_waitcnt lgkmcnt(6)
	v_lshl_or_b32 v44, v45, 16, v44
	s_waitcnt lgkmcnt(4)
	v_lshl_or_b32 v45, v47, 16, v46
	s_waitcnt lgkmcnt(2)
	v_lshl_or_b32 v46, v140, 16, v87
	s_waitcnt lgkmcnt(0)
	v_lshl_or_b32 v47, v142, 16, v141
	s_nop 1
	v_mov_b32_e32 v140, v164
	v_mov_b32_e32 v141, v165
	v_mov_b32_e32 v142, v166
	v_mov_b32_e32 v143, v167
	v_cvt_pk_bf16_f32 v38, v40, v41
	v_cvt_pk_bf16_f32 v39, v42, v43
	s_nop 1
	v_mfma_f32_32x32x16_bf16 v[16:31], v[44:47], v[36:39], v[16:31]
	s_waitcnt vmcnt(3)
	v_mfma_f32_32x32x16_bf16 v[32:47], v[0:3], v[32:35], 0
	s_nop 1
	v_mov_b32_e32 v0, v170
	v_mov_b32_e32 v1, v171
	v_mov_b32_e32 v2, v172
	v_mov_b32_e32 v3, v173
	s_waitcnt vmcnt(3)
	v_mfma_f32_32x32x16_bf16 v[32:47], v[4:7], v[52:55], v[32:47]
	s_nop 1
	v_mov_b32_e32 v4, v228
	v_mov_b32_e32 v5, v229
	v_mov_b32_e32 v6, v230
	v_mov_b32_e32 v7, v231
	s_nop 1
	v_mov_b32_e32 v52, v234
	v_mov_b32_e32 v53, v235
	v_mov_b32_e32 v54, v236
	v_mov_b32_e32 v55, v237
	v_mfma_f32_32x32x16_bf16 v[32:47], v[76:79], v[56:59], v[32:47]
	v_mul_f32_e32 v56, s4, v115
	v_mul_f32_e32 v57, s4, v117
	v_mul_f32_e32 v58, s4, v119
	v_mul_f32_e32 v59, s4, v121
	v_exp_f32_e32 v56, v56
	v_exp_f32_e32 v57, v57
	v_exp_f32_e32 v58, v58
	s_waitcnt vmcnt(4)
	v_mfma_f32_32x32x16_bf16 v[32:47], v[136:139], v[60:63], v[32:47]
	v_exp_f32_e32 v59, v59
	v_mul_f32_e32 v60, s4, v123
	v_mul_f32_e32 v61, s4, v125
	v_mul_f32_e32 v62, s4, v127
	v_mul_f32_e32 v63, s4, v129
	v_exp_f32_e32 v60, v60
	v_exp_f32_e32 v61, v61
	s_waitcnt vmcnt(3)
	v_mfma_f32_32x32x16_bf16 v[32:47], v[140:143], v[64:67], v[32:47]
	v_exp_f32_e32 v62, v62
	v_exp_f32_e32 v63, v63
	s_waitcnt vmcnt(2)
	v_mfma_f32_32x32x16_bf16 v[32:47], v[0:3], v[68:71], v[32:47]
	v_mul_f32_e64 v0, v56, v8
	v_mul_f32_e64 v1, v57, v9
	v_mul_f32_e64 v2, v58, v10
	v_mul_f32_e64 v3, v59, v11
	v_mul_f32_e64 v8, v60, v12
	v_mul_f32_e64 v9, v61, v13
	v_pk_mul_f32 v[10:11], v[62:63], v[14:15]
	v_cvt_pk_bf16_f32 v0, v0, v1
	v_cvt_pk_bf16_f32 v1, v2, v3
	s_waitcnt vmcnt(1)
	v_mfma_f32_32x32x16_bf16 v[32:47], v[4:7], v[72:75], v[32:47]
	ds_read_u16 v2, v130 offset:47872
	ds_read_u16 v3, v130 offset:48144
	ds_read_u16 v5, v130 offset:48416
	ds_read_u16 v6, v130 offset:48688
	ds_read_u16 v7, v130 offset:50048
	ds_read_u16 v12, v130 offset:50320
	ds_read_u16 v13, v130 offset:50592
	ds_read_u16 v14, v130 offset:50864
	s_waitcnt lgkmcnt(6)
	v_lshl_or_b32 v4, v3, 16, v2
	s_waitcnt lgkmcnt(4)
	v_lshl_or_b32 v5, v6, 16, v5
	s_waitcnt lgkmcnt(2)
	v_lshl_or_b32 v6, v12, 16, v7
	v_cvt_pk_bf16_f32 v2, v8, v9
	s_waitcnt lgkmcnt(0)
	v_lshl_or_b32 v7, v14, 16, v13
	v_cvt_pk_bf16_f32 v3, v10, v11
	s_waitcnt vmcnt(0)
	v_mfma_f32_32x32x16_bf16 v[32:47], v[52:55], v[48:51], v[32:47]
	v_mul_f32_e32 v8, s4, v95
	v_exp_f32_e32 v8, v8
	v_mfma_f32_32x32x16_bf16 v[16:31], v[4:7], v[0:3], v[16:31]
	s_nop 11
	v_pk_fma_f32 v[32:33], v[8:9], v[32:33], v[16:17] op_sel_hi:[0,1,1]
	v_pk_mul_f32 v[0:1], v[32:33], v[32:33]
	v_pk_fma_f32 v[18:19], v[8:9], v[34:35], v[18:19] op_sel_hi:[0,1,1]
	v_pk_mul_f32 v[2:3], v[18:19], v[18:19]
	v_add_f32_e32 v0, v0, v1
	v_pk_fma_f32 v[14:15], v[8:9], v[36:37], v[20:21] op_sel_hi:[0,1,1]
	v_add_f32_e32 v0, v2, v0
	v_pk_mul_f32 v[20:21], v[14:15], v[14:15]
	v_add_f32_e32 v0, v3, v0
	v_pk_fma_f32 v[16:17], v[8:9], v[38:39], v[22:23] op_sel_hi:[0,1,1]
	v_add_f32_e32 v0, v20, v0
	v_pk_mul_f32 v[22:23], v[16:17], v[16:17]
	v_add_f32_e32 v0, v21, v0
	v_pk_fma_f32 v[10:11], v[8:9], v[40:41], v[24:25] op_sel_hi:[0,1,1]
	v_add_f32_e32 v0, v22, v0
	v_pk_mul_f32 v[24:25], v[10:11], v[10:11]
	v_add_f32_e32 v0, v23, v0
	v_pk_fma_f32 v[12:13], v[8:9], v[42:43], v[26:27] op_sel_hi:[0,1,1]
	v_add_f32_e32 v0, v24, v0
	v_pk_mul_f32 v[26:27], v[12:13], v[12:13]
	v_add_f32_e32 v0, v25, v0
	v_pk_fma_f32 v[4:5], v[8:9], v[44:45], v[28:29] op_sel_hi:[0,1,1]
	v_add_f32_e32 v0, v26, v0
	v_pk_mul_f32 v[28:29], v[4:5], v[4:5]
	v_add_f32_e32 v0, v27, v0
	v_and_b32_e32 v2, 64, v254
	v_pk_fma_f32 v[6:7], v[8:9], v[46:47], v[30:31] op_sel_hi:[0,1,1]
	v_add_f32_e32 v0, v28, v0
	v_xor_b32_e32 v1, 32, v254
	v_add_u32_e32 v2, 64, v2
	v_pk_mul_f32 v[8:9], v[6:7], v[6:7]
	v_add_f32_e32 v0, v29, v0
	v_cmp_lt_i32_e64 s[4:5], v1, v2
	v_add_f32_e32 v0, v8, v0
	v_add_f32_e32 v0, v9, v0
	v_cndmask_b32_e64 v1, v254, v1, s[4:5]
	v_lshlrev_b32_e32 v1, 2, v1
	ds_bpermute_b32 v1, v1, v0
	s_and_saveexec_b64 s[4:5], vcc
	s_cbranch_execz .LBB0_580
	s_waitcnt lgkmcnt(0)
	v_add_f32_e32 v0, v0, v1
	ds_write_b32 v135, v0 offset:52224
	s_branch .LBB0_580
